# P4 A-combine loop fully unrolled (3 trips at grid 256) and software-pipelined: next trip's 14 loads issued before the current trip's compute
# baseline (speedup 1.0000x reference)
.LBB0_482:
	v_readlane_b32 s4, v254, 8
	s_nop 1
	v_add_u32_e32 v82, s4, v158
	s_mov_b32 s4, 0xc0000
	v_cmp_gt_i32_e32 vcc, s4, v82
	s_and_saveexec_b64 s[6:7], vcc
	s_mov_b32 s53, 0x2aaaaaab
	s_mov_b32 s62, s68
	s_cbranch_execz .LBB0_487
	v_readlane_b32 s4, v254, 9
	v_lshlrev_b32_e32 v0, 3, v82
	s_lshl_b32 s8, s4, 3
	s_mov_b64 s[10:11], 0
	v_mov_b32_e32 v22, v82
	s_cmp_lg_u32 s3, 0x100
	s_cbranch_scc1 .LBB0_485
	v_readlane_b32 s41, v254, 9
	v_mul_hi_i32 v2, v22, s53
	v_lshrrev_b32_e32 v3, 31, v2
	v_ashrrev_i32_e32 v2, 4, v2
	v_add_u32_e32 v28, v2, v3
	s_movk_i32 s4, 0xfd00
	v_mad_u64_u32 v[2:3], s[4:5], v28, s4, v[0:1]
	v_ashrrev_i32_e32 v3, 31, v2
	v_readlane_b32 s24, v252, 37
	v_lshlrev_b64 v[30:31], 1, v[2:3]
	v_readlane_b32 s25, v252, 38
	s_movk_i32 s14, 0x600
	s_mov_b32 s26, 0xc00000
	v_lshl_add_u64 v[2:3], s[24:25], 0, v[30:31]
	v_mad_i64_i32 v[2:3], s[4:5], v28, s14, v[2:3]
	v_add_co_u32_e32 v4, vcc, s26, v2
	s_mov_b32 s27, 0x1800000
	s_nop 0
	v_addc_co_u32_e32 v5, vcc, 0, v3, vcc
	global_load_dwordx4 v[32:35], v[2:3], off
	global_load_dwordx4 v[36:39], v[4:5], off
	v_add_co_u32_e32 v2, vcc, s27, v2
	s_mov_b32 s36, 0xc0000
	s_nop 0
	v_addc_co_u32_e32 v3, vcc, 0, v3, vcc
	global_load_dwordx4 v[40:43], v[2:3], off
	v_mov_b64_e32 v[2:3], s[0:1]
	v_mad_i64_i32 v[4:5], s[4:5], v28, s35, v[2:3]
	v_readlane_b32 s4, v254, 7
	s_movk_i32 s9, 0x60
	v_lshl_add_u64 v[4:5], v[4:5], 0, v[30:31]
	v_add_u32_e32 v6, s4, v22
	v_cmp_gt_i32_e64 s[4:5], s36, v6
	v_add_co_u32_e32 v4, vcc, s34, v4
	s_nop 0
	v_cndmask_b32_e64 v6, v82, v6, s[4:5]
	v_mul_hi_i32 v7, v6, s53
	v_lshrrev_b32_e32 v8, 31, v7
	v_ashrrev_i32_e32 v7, 4, v7
	v_add_u32_e32 v24, v7, v8
	v_mul_lo_u32 v7, v24, s9
	v_sub_u32_e32 v23, v6, v7
	v_lshlrev_b32_e32 v26, 3, v23
	v_ashrrev_i32_e32 v27, 31, v26
	v_lshlrev_b64 v[44:45], 1, v[26:27]
	v_addc_co_u32_e32 v5, vcc, 0, v5, vcc
	v_lshl_add_u64 v[6:7], s[24:25], 0, v[44:45]
	v_mad_i64_i32 v[6:7], s[24:25], v24, s14, v[6:7]
	global_load_dwordx4 v[18:21], v[4:5], off offset:512
	s_waitcnt lgkmcnt(0)
	global_load_dwordx4 v[14:17], v[6:7], off
	v_add_co_u32_e32 v4, vcc, s26, v6
	v_mad_i64_i32 v[2:3], s[24:25], v24, s35, v[2:3]
	s_movk_i32 s9, 0xffa0
	v_addc_co_u32_e32 v5, vcc, 0, v7, vcc
	v_lshl_add_u64 v[2:3], v[2:3], 0, v[44:45]
	v_mad_u64_u32 v[44:45], s[24:25], v28, s9, v[22:23]
	global_load_dwordx4 v[10:13], v[4:5], off
	v_add_co_u32_e32 v4, vcc, s27, v6
	v_ashrrev_i32_e32 v44, 3, v44
	v_readlane_b32 s26, v252, 39
	v_addc_co_u32_e32 v5, vcc, 0, v7, vcc
	v_ashrrev_i32_e32 v45, 31, v44
	v_readlane_b32 s27, v252, 40
	v_add_co_u32_e32 v2, vcc, s34, v2
	s_nop 0
	v_lshl_add_u64 v[44:45], v[44:45], 2, s[26:27]
	v_addc_co_u32_e32 v3, vcc, 0, v3, vcc
	v_mad_i64_i32 v[44:45], s[24:25], v28, 48, v[44:45]
	s_mov_b32 s9, 0x60000
	v_add_co_u32_e32 v46, vcc, s9, v44
	global_load_dwordx4 v[6:9], v[4:5], off
	s_nop 0
	v_addc_co_u32_e32 v47, vcc, 0, v45, vcc
	global_load_dword v25, v[44:45], off
	global_load_dword v50, v[46:47], off
	v_ashrrev_i32_e32 v46, 3, v23
	global_load_dwordx4 v[2:5], v[2:3], off offset:512
	v_ashrrev_i32_e32 v47, 31, v46
	v_add_co_u32_e32 v44, vcc, s36, v44
	v_lshl_add_u64 v[46:47], v[46:47], 2, s[26:27]
	s_nop 0
	v_addc_co_u32_e32 v45, vcc, 0, v45, vcc
	v_mad_i64_i32 v[46:47], s[24:25], v24, 48, v[46:47]
	v_add_co_u32_e32 v48, vcc, s9, v46
	global_load_dword v44, v[44:45], off
	s_nop 0
	v_addc_co_u32_e32 v49, vcc, 0, v47, vcc
	global_load_dword v23, v[48:49], off
	s_nop 0
	global_load_dword v48, v[46:47], off
	v_add_co_u32_e32 v46, vcc, s36, v46
	v_ashrrev_i32_e32 v29, 31, v28
	s_nop 0
	v_addc_co_u32_e32 v47, vcc, 0, v47, vcc
	global_load_dword v46, v[46:47], off
	v_add_u32_e32 v206, s41, v22
	v_mov_b32_e32 v239, 0
	v_mov_b32_e32 v241, 1.0
	v_lshlrev_b32_e32 v238, 3, v206
	v_mul_hi_i32 v144, v206, s53
	v_lshrrev_b32_e32 v145, 31, v144
	v_ashrrev_i32_e32 v144, 4, v144
	v_add_u32_e32 v212, v144, v145
	s_movk_i32 s38, 0xfd00
	v_mad_u64_u32 v[144:145], s[38:39], v212, s38, v[238:239]
	v_ashrrev_i32_e32 v145, 31, v144
	v_readlane_b32 s24, v252, 37
	v_lshlrev_b64 v[214:215], 1, v[144:145]
	v_readlane_b32 s25, v252, 38
	s_movk_i32 s14, 0x600
	s_mov_b32 s26, 0xc00000
	v_lshl_add_u64 v[144:145], s[24:25], 0, v[214:215]
	v_mad_i64_i32 v[144:145], s[38:39], v212, s14, v[144:145]
	v_add_co_u32_e32 v146, vcc, s26, v144
	s_mov_b32 s27, 0x1800000
	s_nop 0
	v_addc_co_u32_e32 v147, vcc, 0, v145, vcc
	global_load_dwordx4 v[216:219], v[144:145], off
	global_load_dwordx4 v[220:223], v[146:147], off
	v_add_co_u32_e32 v144, vcc, s27, v144
	s_mov_b32 s36, 0xc0000
	s_nop 0
	v_addc_co_u32_e32 v145, vcc, 0, v145, vcc
	global_load_dwordx4 v[224:227], v[144:145], off
	v_mov_b64_e32 v[144:145], s[0:1]
	v_mad_i64_i32 v[146:147], s[38:39], v212, s35, v[144:145]
	v_readlane_b32 s38, v254, 7
	s_movk_i32 s9, 0x60
	v_lshl_add_u64 v[146:147], v[146:147], 0, v[214:215]
	v_add_u32_e32 v148, s38, v206
	v_cmp_gt_i32_e64 s[38:39], s36, v148
	v_add_co_u32_e32 v146, vcc, s34, v146
	s_nop 0
	v_cndmask_b32_e64 v148, v82, v148, s[38:39]
	v_mul_hi_i32 v149, v148, s53
	v_lshrrev_b32_e32 v150, 31, v149
	v_ashrrev_i32_e32 v149, 4, v149
	v_add_u32_e32 v208, v149, v150
	v_mul_lo_u32 v149, v208, s9
	v_sub_u32_e32 v207, v148, v149
	v_lshlrev_b32_e32 v210, 3, v207
	v_ashrrev_i32_e32 v211, 31, v210
	v_lshlrev_b64 v[228:229], 1, v[210:211]
	v_addc_co_u32_e32 v147, vcc, 0, v147, vcc
	v_lshl_add_u64 v[148:149], s[24:25], 0, v[228:229]
	v_mad_i64_i32 v[148:149], s[24:25], v208, s14, v[148:149]
	global_load_dwordx4 v[202:205], v[146:147], off offset:512
	s_waitcnt lgkmcnt(0)
	global_load_dwordx4 v[156:159], v[148:149], off
	v_add_co_u32_e32 v146, vcc, s26, v148
	v_mad_i64_i32 v[144:145], s[24:25], v208, s35, v[144:145]
	s_movk_i32 s9, 0xffa0
	v_addc_co_u32_e32 v147, vcc, 0, v149, vcc
	v_lshl_add_u64 v[144:145], v[144:145], 0, v[228:229]
	v_mad_u64_u32 v[228:229], s[24:25], v212, s9, v[206:207]
	global_load_dwordx4 v[152:155], v[146:147], off
	v_add_co_u32_e32 v146, vcc, s27, v148
	v_ashrrev_i32_e32 v228, 3, v228
	v_readlane_b32 s26, v252, 39
	v_addc_co_u32_e32 v147, vcc, 0, v149, vcc
	v_ashrrev_i32_e32 v229, 31, v228
	v_readlane_b32 s27, v252, 40
	v_add_co_u32_e32 v144, vcc, s34, v144
	s_nop 0
	v_lshl_add_u64 v[228:229], v[228:229], 2, s[26:27]
	v_addc_co_u32_e32 v145, vcc, 0, v145, vcc
	v_mad_i64_i32 v[228:229], s[24:25], v212, 48, v[228:229]
	s_mov_b32 s9, 0x60000
	v_add_co_u32_e32 v230, vcc, s9, v228
	global_load_dwordx4 v[148:151], v[146:147], off
	s_nop 0
	v_addc_co_u32_e32 v231, vcc, 0, v229, vcc
	global_load_dword v209, v[228:229], off
	global_load_dword v234, v[230:231], off
	v_ashrrev_i32_e32 v230, 3, v207
	global_load_dwordx4 v[144:147], v[144:145], off offset:512
	v_ashrrev_i32_e32 v231, 31, v230
	v_add_co_u32_e32 v228, vcc, s36, v228
	v_lshl_add_u64 v[230:231], v[230:231], 2, s[26:27]
	s_nop 0
	v_addc_co_u32_e32 v229, vcc, 0, v229, vcc
	v_mad_i64_i32 v[230:231], s[24:25], v208, 48, v[230:231]
	v_add_co_u32_e32 v232, vcc, s9, v230
	global_load_dword v228, v[228:229], off
	s_nop 0
	v_addc_co_u32_e32 v233, vcc, 0, v231, vcc
	global_load_dword v207, v[232:233], off
	s_nop 0
	global_load_dword v232, v[230:231], off
	v_add_co_u32_e32 v230, vcc, s36, v230
	v_ashrrev_i32_e32 v213, 31, v212
	s_nop 0
	v_addc_co_u32_e32 v231, vcc, 0, v231, vcc
	global_load_dword v230, v[230:231], off
	s_waitcnt vmcnt(24)
	s_nop 0
	v_lshlrev_b32_e32 v45, 16, v32
	v_and_b32_e32 v32, 0xffff0000, v32
	v_add_f32_e32 v32, 0, v32
	v_lshlrev_b32_e32 v47, 16, v33
	v_and_b32_e32 v33, 0xffff0000, v33
	v_lshlrev_b32_e32 v52, 16, v36
	v_and_b32_e32 v36, 0xffff0000, v36
	v_add_f32_e32 v33, 0, v33
	v_lshlrev_b32_e32 v49, 16, v34
	v_and_b32_e32 v34, 0xffff0000, v34
	v_add_f32_e32 v32, v32, v36
	v_lshlrev_b32_e32 v36, 16, v37
	v_and_b32_e32 v37, 0xffff0000, v37
	v_add_f32_e32 v34, 0, v34
	v_lshlrev_b32_e32 v51, 16, v35
	v_and_b32_e32 v35, 0xffff0000, v35
	v_add_f32_e32 v33, v33, v37
	v_lshlrev_b32_e32 v37, 16, v38
	v_and_b32_e32 v38, 0xffff0000, v38
	v_add_f32_e32 v35, 0, v35
	v_add_f32_e32 v34, v34, v38
	v_lshlrev_b32_e32 v38, 16, v39
	v_and_b32_e32 v39, 0xffff0000, v39
	v_add_f32_e32 v47, 0, v47
	v_add_f32_e32 v35, v35, v39
	v_lshlrev_b32_e32 v39, 16, v40
	v_and_b32_e32 v40, 0xffff0000, v40
	v_add_f32_e32 v36, v47, v36
	v_add_f32_e32 v32, v32, v40
	v_lshlrev_b32_e32 v40, 16, v41
	v_add_f32_e32 v49, 0, v49
	v_add_f32_e32 v36, v36, v40
	v_and_b32_e32 v40, 0xffff0000, v41
	v_add_f32_e32 v37, v49, v37
	v_add_f32_e32 v33, v33, v40
	v_lshlrev_b32_e32 v40, 16, v42
	v_lshlrev_b32_e32 v41, 16, v18
	v_add_f32_e32 v37, v37, v40
	v_and_b32_e32 v40, 0xffff0000, v42
	v_mul_f32_e32 v42, 0xbfb8aa3b, v41
	v_exp_f32_e32 v42, v42
	v_add_f32_e32 v51, 0, v51
	v_add_f32_e32 v38, v51, v38
	v_add_f32_e32 v34, v34, v40
	v_lshlrev_b32_e32 v40, 16, v43
	v_add_f32_e32 v45, 0, v45
	v_add_f32_e32 v38, v38, v40
	v_add_f32_e32 v40, 1.0, v42
	v_add_f32_e32 v45, v45, v52
	v_div_scale_f32 v42, s[24:25], v40, v40, v41
	v_add_f32_e32 v39, v45, v39
	v_rcp_f32_e32 v45, v42
	v_and_b32_e32 v18, 0xffff0000, v18
	s_waitcnt vmcnt(19)
	v_add_f32_e32 v176, v25, v50
	v_mul_f32_e32 v47, 0xbfb8aa3b, v18
	v_fma_f32 v25, -v42, v45, 1.0
	v_and_b32_e32 v43, 0xffff0000, v43
	v_fmac_f32_e32 v45, v25, v45
	v_div_scale_f32 v25, vcc, v41, v40, v41
	v_exp_f32_e32 v47, v47
	v_add_f32_e32 v35, v35, v43
	v_mul_f32_e32 v43, v25, v45
	v_fma_f32 v49, -v42, v43, v25
	v_fmac_f32_e32 v43, v49, v45
	v_fma_f32 v25, -v42, v43, v25
	v_add_f32_e32 v42, 1.0, v47
	v_div_scale_f32 v47, s[24:25], v42, v42, v18
	v_rcp_f32_e32 v49, v47
	v_div_fmas_f32 v25, v25, v45, v43
	v_lshlrev_b32_e32 v43, 16, v19
	v_mul_f32_e32 v45, 0xbfb8aa3b, v43
	v_div_fixup_f32 v25, v25, v40, v41
	v_fma_f32 v40, -v47, v49, 1.0
	v_exp_f32_e32 v45, v45
	v_fmac_f32_e32 v49, v40, v49
	v_div_scale_f32 v40, vcc, v18, v42, v18
	v_mul_f32_e32 v41, v40, v49
	v_fma_f32 v50, -v47, v41, v40
	v_fmac_f32_e32 v41, v50, v49
	v_add_f32_e32 v45, 1.0, v45
	v_fma_f32 v40, -v47, v41, v40
	v_div_scale_f32 v47, s[24:25], v45, v45, v43
	v_rcp_f32_e32 v50, v47
	v_div_fmas_f32 v40, v40, v49, v41
	v_and_b32_e32 v19, 0xffff0000, v19
	v_div_fixup_f32 v40, v40, v42, v18
	v_mul_f32_e32 v42, 0xbfb8aa3b, v19
	v_fma_f32 v18, -v47, v50, 1.0
	v_exp_f32_e32 v42, v42
	v_fmac_f32_e32 v50, v18, v50
	v_div_scale_f32 v18, vcc, v43, v45, v43
	v_mul_f32_e32 v41, v18, v50
	v_fma_f32 v49, -v47, v41, v18
	v_fmac_f32_e32 v41, v49, v50
	v_add_f32_e32 v42, 1.0, v42
	v_fma_f32 v18, -v47, v41, v18
	v_div_scale_f32 v47, s[24:25], v42, v42, v19
	v_rcp_f32_e32 v49, v47
	v_div_fmas_f32 v18, v18, v50, v41
	v_div_fixup_f32 v41, v18, v45, v43
	v_lshlrev_b32_e32 v45, 16, v20
	v_fma_f32 v18, -v47, v49, 1.0
	v_mul_f32_e32 v50, 0xbfb8aa3b, v45
	v_fmac_f32_e32 v49, v18, v49
	v_div_scale_f32 v18, vcc, v19, v42, v19
	v_exp_f32_e32 v50, v50
	v_mul_f32_e32 v43, v18, v49
	v_fma_f32 v51, -v47, v43, v18
	v_fmac_f32_e32 v43, v51, v49
	v_fma_f32 v18, -v47, v43, v18
	v_add_f32_e32 v47, 1.0, v50
	v_div_scale_f32 v50, s[24:25], v47, v47, v45
	v_rcp_f32_e32 v51, v50
	v_and_b32_e32 v20, 0xffff0000, v20
	v_div_fmas_f32 v18, v18, v49, v43
	v_mul_f32_e32 v43, 0xbfb8aa3b, v20
	v_exp_f32_e32 v43, v43
	v_div_fixup_f32 v42, v18, v42, v19
	v_fma_f32 v18, -v50, v51, 1.0
	v_fmac_f32_e32 v51, v18, v51
	v_div_scale_f32 v18, vcc, v45, v47, v45
	v_mul_f32_e32 v19, v18, v51
	v_fma_f32 v49, -v50, v19, v18
	v_add_f32_e32 v43, 1.0, v43
	v_fmac_f32_e32 v19, v49, v51
	v_div_scale_f32 v49, s[24:25], v43, v43, v20
	v_fma_f32 v18, -v50, v19, v18
	v_rcp_f32_e32 v50, v49
	v_div_fmas_f32 v18, v18, v51, v19
	v_lshlrev_b32_e32 v52, 16, v21
	v_div_fixup_f32 v47, v18, v47, v45
	v_fma_f32 v18, -v49, v50, 1.0
	v_mul_f32_e32 v19, 0xbfb8aa3b, v52
	v_fmac_f32_e32 v50, v18, v50
	v_div_scale_f32 v18, vcc, v20, v43, v20
	v_exp_f32_e32 v45, v19
	v_mul_f32_e32 v51, v18, v50
	v_fma_f32 v19, -v49, v51, v18
	v_fmac_f32_e32 v51, v19, v50
	v_fma_f32 v49, -v49, v51, v18
	s_waitcnt vmcnt(17)
	v_pk_add_f32 v[18:19], v[176:177], v[44:45]
	v_div_fmas_f32 v49, v49, v50, v51
	v_div_scale_f32 v44, s[24:25], v19, v19, v52
	v_rcp_f32_e32 v45, v44
	v_div_fixup_f32 v20, v49, v43, v20
	v_and_b32_e32 v21, 0xffff0000, v21
	v_fma_f32 v43, -v44, v45, 1.0
	v_fmac_f32_e32 v45, v43, v45
	v_div_scale_f32 v43, vcc, v52, v19, v52
	v_mul_f32_e32 v49, v43, v45
	v_fma_f32 v50, -v44, v49, v43
	v_fmac_f32_e32 v49, v50, v45
	v_fma_f32 v43, -v44, v49, v43
	v_div_scale_f32 v44, s[24:25], v18, v18, 1.0
	v_rcp_f32_e32 v50, v44
	v_div_fmas_f32 v43, v43, v45, v49
	v_div_fixup_f32 v43, v43, v19, v52
	v_lshlrev_b64 v[28:29], 12, v[28:29]
	v_fma_f32 v19, -v44, v50, 1.0
	v_fmac_f32_e32 v50, v19, v50
	v_div_scale_f32 v19, vcc, 1.0, v18, 1.0
	v_mul_f32_e32 v45, v19, v50
	v_fma_f32 v49, -v44, v45, v19
	v_fmac_f32_e32 v45, v49, v50
	v_fma_f32 v19, -v44, v45, v19
	v_div_fmas_f32 v19, v19, v50, v45
	v_div_fixup_f32 v44, v19, v18, 1.0
	v_mul_f32_e32 v18, v44, v39
	v_mul_f32_e32 v19, v44, v32
	v_mul_f32_e32 v18, v18, v25
	v_mul_f32_e32 v19, v19, v40
	v_mul_f32_e32 v32, 0xbfb8aa3b, v21
	v_cvt_pk_bf16_f32 v18, v18, v19
	v_mul_f32_e32 v19, v44, v36
	v_mul_f32_e32 v25, v44, v33
	v_exp_f32_e32 v32, v32
	v_mul_f32_e32 v19, v19, v41
	v_mul_f32_e32 v25, v25, v42
	v_cvt_pk_bf16_f32 v19, v19, v25
	v_mul_f32_e32 v25, v44, v37
	v_mul_f32_e32 v33, v44, v34
	v_mul_f32_e32 v25, v25, v47
	v_mul_f32_e32 v20, v33, v20
	v_cvt_pk_bf16_f32 v20, v25, v20
	v_add_f32_e32 v25, 1.0, v32
	v_div_scale_f32 v32, s[24:25], v25, v25, v21
	v_rcp_f32_e32 v33, v32
	v_mul_f32_e32 v34, v44, v38
	v_mul_f32_e32 v35, v44, v35
	v_lshl_add_u64 v[28:29], s[12:13], 0, v[28:29]
	v_fma_f32 v36, -v32, v33, 1.0
	v_fmac_f32_e32 v33, v36, v33
	v_div_scale_f32 v36, vcc, v21, v25, v21
	v_mul_f32_e32 v37, v36, v33
	v_fma_f32 v38, -v32, v37, v36
	v_fmac_f32_e32 v37, v38, v33
	v_fma_f32 v32, -v32, v37, v36
	v_div_fmas_f32 v32, v32, v33, v37
	v_div_fixup_f32 v21, v32, v25, v21
	v_mul_f32_e32 v21, v35, v21
	v_lshl_add_u64 v[28:29], v[28:29], 0, v[30:31]
	v_mul_f32_e32 v34, v34, v43
	v_cvt_pk_bf16_f32 v21, v34, v21
	global_store_dwordx4 v[28:29], v[18:21], off
	v_lshlrev_b32_e32 v25, 16, v10
	v_and_b32_e32 v10, 0xffff0000, v10
	v_lshlrev_b32_e32 v18, 16, v14
	v_and_b32_e32 v14, 0xffff0000, v14
	v_add_f32_e32 v14, 0, v14
	v_lshlrev_b32_e32 v19, 16, v15
	v_and_b32_e32 v15, 0xffff0000, v15
	v_add_f32_e32 v15, 0, v15
	v_lshlrev_b32_e32 v20, 16, v16
	v_and_b32_e32 v16, 0xffff0000, v16
	v_add_f32_e32 v10, v14, v10
	v_lshlrev_b32_e32 v14, 16, v11
	v_and_b32_e32 v11, 0xffff0000, v11
	v_add_f32_e32 v16, 0, v16
	v_lshlrev_b32_e32 v21, 16, v17
	v_and_b32_e32 v17, 0xffff0000, v17
	v_add_f32_e32 v11, v15, v11
	v_lshlrev_b32_e32 v15, 16, v12
	v_and_b32_e32 v12, 0xffff0000, v12
	v_add_f32_e32 v17, 0, v17
	v_add_f32_e32 v12, v16, v12
	v_lshlrev_b32_e32 v16, 16, v13
	v_and_b32_e32 v13, 0xffff0000, v13
	v_add_f32_e32 v19, 0, v19
	v_add_f32_e32 v13, v17, v13
	v_lshlrev_b32_e32 v17, 16, v6
	v_and_b32_e32 v6, 0xffff0000, v6
	v_add_f32_e32 v14, v19, v14
	v_add_f32_e32 v6, v10, v6
	v_lshlrev_b32_e32 v10, 16, v7
	v_add_f32_e32 v20, 0, v20
	v_add_f32_e32 v10, v14, v10
	v_and_b32_e32 v7, 0xffff0000, v7
	s_waitcnt vmcnt(16)
	v_add_f32_e32 v14, v48, v23
	v_add_f32_e32 v18, 0, v18
	v_add_f32_e32 v15, v20, v15
	v_add_f32_e32 v7, v11, v7
	v_lshlrev_b32_e32 v11, 16, v8
	s_waitcnt vmcnt(15)
	v_add_f32_e32 v14, v14, v46
	v_add_f32_e32 v18, v18, v25
	v_add_f32_e32 v11, v15, v11
	v_div_scale_f32 v15, s[24:25], v14, v14, 1.0
	v_add_f32_e32 v17, v18, v17
	v_rcp_f32_e32 v18, v15
	v_and_b32_e32 v8, 0xffff0000, v8
	v_add_f32_e32 v8, v12, v8
	v_lshlrev_b32_e32 v12, 16, v9
	v_and_b32_e32 v9, 0xffff0000, v9
	v_lshlrev_b32_e32 v19, 16, v2
	v_add_f32_e32 v21, 0, v21
	v_add_f32_e32 v9, v13, v9
	v_fma_f32 v13, -v15, v18, 1.0
	v_mul_f32_e32 v20, 0xbfb8aa3b, v19
	v_add_f32_e32 v16, v21, v16
	v_fmac_f32_e32 v18, v13, v18
	v_div_scale_f32 v13, vcc, 1.0, v14, 1.0
	v_exp_f32_e32 v20, v20
	v_add_f32_e32 v12, v16, v12
	v_mul_f32_e32 v16, v13, v18
	v_fma_f32 v21, -v15, v16, v13
	v_fmac_f32_e32 v16, v21, v18
	v_fma_f32 v13, -v15, v16, v13
	v_add_f32_e32 v15, 1.0, v20
	v_div_scale_f32 v20, s[24:25], v15, v15, v19
	v_rcp_f32_e32 v21, v20
	v_div_fmas_f32 v13, v13, v18, v16
	v_div_fixup_f32 v13, v13, v14, 1.0
	v_mul_f32_e32 v14, v13, v17
	v_fma_f32 v16, -v20, v21, 1.0
	v_fmac_f32_e32 v21, v16, v21
	v_div_scale_f32 v16, vcc, v19, v15, v19
	v_mul_f32_e32 v17, v16, v21
	v_fma_f32 v18, -v20, v17, v16
	v_and_b32_e32 v2, 0xffff0000, v2
	v_fmac_f32_e32 v17, v18, v21
	v_mul_f32_e32 v18, 0xbfb8aa3b, v2
	v_exp_f32_e32 v18, v18
	v_fma_f32 v16, -v20, v17, v16
	v_div_fmas_f32 v16, v16, v21, v17
	v_div_fixup_f32 v15, v16, v15, v19
	v_add_f32_e32 v17, 1.0, v18
	v_div_scale_f32 v18, s[24:25], v17, v17, v2
	v_rcp_f32_e32 v20, v18
	v_mul_f32_e32 v14, v14, v15
	v_mul_f32_e32 v6, v13, v6
	v_mul_f32_e32 v7, v13, v7
	v_fma_f32 v15, -v18, v20, 1.0
	v_fmac_f32_e32 v20, v15, v20
	v_div_scale_f32 v15, vcc, v2, v17, v2
	v_mul_f32_e32 v16, v15, v20
	v_fma_f32 v19, -v18, v16, v15
	v_fmac_f32_e32 v16, v19, v20
	v_fma_f32 v15, -v18, v16, v15
	v_lshlrev_b32_e32 v18, 16, v3
	v_mul_f32_e32 v19, 0xbfb8aa3b, v18
	v_exp_f32_e32 v19, v19
	v_div_fmas_f32 v15, v15, v20, v16
	v_div_fixup_f32 v2, v15, v17, v2
	v_mul_f32_e32 v2, v6, v2
	v_add_f32_e32 v15, 1.0, v19
	v_div_scale_f32 v16, s[24:25], v15, v15, v18
	v_rcp_f32_e32 v17, v16
	v_mul_f32_e32 v6, v13, v10
	v_cvt_pk_bf16_f32 v2, v14, v2
	v_and_b32_e32 v3, 0xffff0000, v3
	v_fma_f32 v10, -v16, v17, 1.0
	v_fmac_f32_e32 v17, v10, v17
	v_div_scale_f32 v10, vcc, v18, v15, v18
	v_mul_f32_e32 v14, v10, v17
	v_fma_f32 v19, -v16, v14, v10
	v_fmac_f32_e32 v14, v19, v17
	v_mul_f32_e32 v19, 0xbfb8aa3b, v3
	v_exp_f32_e32 v19, v19
	v_fma_f32 v10, -v16, v14, v10
	v_div_fmas_f32 v10, v10, v17, v14
	v_div_fixup_f32 v10, v10, v15, v18
	v_add_f32_e32 v14, 1.0, v19
	v_div_scale_f32 v16, s[24:25], v14, v14, v3
	v_rcp_f32_e32 v17, v16
	v_mul_f32_e32 v6, v6, v10
	v_fma_f32 v10, -v16, v17, 1.0
	v_fmac_f32_e32 v17, v10, v17
	v_div_scale_f32 v10, vcc, v3, v14, v3
	v_mul_f32_e32 v15, v10, v17
	v_fma_f32 v18, -v16, v15, v10
	v_fmac_f32_e32 v15, v18, v17
	v_fma_f32 v10, -v16, v15, v10
	v_lshlrev_b32_e32 v16, 16, v4
	v_mul_f32_e32 v18, 0xbfb8aa3b, v16
	v_exp_f32_e32 v18, v18
	v_div_fmas_f32 v10, v10, v17, v15
	v_div_fixup_f32 v3, v10, v14, v3
	v_mul_f32_e32 v3, v7, v3
	v_add_f32_e32 v10, 1.0, v18
	v_div_scale_f32 v14, s[24:25], v10, v10, v16
	v_rcp_f32_e32 v15, v14
	v_cvt_pk_bf16_f32 v3, v6, v3
	v_mul_f32_e32 v6, v13, v11
	v_and_b32_e32 v4, 0xffff0000, v4
	v_fma_f32 v7, -v14, v15, 1.0
	v_fmac_f32_e32 v15, v7, v15
	v_div_scale_f32 v7, vcc, v16, v10, v16
	v_mul_f32_e32 v11, v7, v15
	v_fma_f32 v17, -v14, v11, v7
	v_fmac_f32_e32 v11, v17, v15
	v_mul_f32_e32 v17, 0xbfb8aa3b, v4
	v_exp_f32_e32 v17, v17
	v_fma_f32 v7, -v14, v11, v7
	v_div_fmas_f32 v7, v7, v15, v11
	v_div_fixup_f32 v7, v7, v10, v16
	v_add_f32_e32 v11, 1.0, v17
	v_div_scale_f32 v14, s[24:25], v11, v11, v4
	v_rcp_f32_e32 v15, v14
	v_mul_f32_e32 v6, v6, v7
	v_mul_f32_e32 v7, v13, v8
	v_fma_f32 v8, -v14, v15, 1.0
	v_fmac_f32_e32 v15, v8, v15
	v_div_scale_f32 v8, vcc, v4, v11, v4
	v_mul_f32_e32 v10, v8, v15
	v_fma_f32 v16, -v14, v10, v8
	v_fmac_f32_e32 v10, v16, v15
	v_fma_f32 v8, -v14, v10, v8
	v_lshlrev_b32_e32 v14, 16, v5
	v_mul_f32_e32 v16, 0xbfb8aa3b, v14
	v_exp_f32_e32 v16, v16
	v_div_fmas_f32 v8, v8, v15, v10
	v_div_fixup_f32 v4, v8, v11, v4
	v_mul_f32_e32 v4, v7, v4
	v_add_f32_e32 v8, 1.0, v16
	v_div_scale_f32 v10, s[24:25], v8, v8, v14
	v_rcp_f32_e32 v11, v10
	v_cvt_pk_bf16_f32 v4, v6, v4
	v_mul_f32_e32 v6, v13, v12
	v_and_b32_e32 v5, 0xffff0000, v5
	v_fma_f32 v7, -v10, v11, 1.0
	v_fmac_f32_e32 v11, v7, v11
	v_div_scale_f32 v7, vcc, v14, v8, v14
	v_mul_f32_e32 v12, v7, v11
	v_fma_f32 v15, -v10, v12, v7
	v_fmac_f32_e32 v12, v15, v11
	v_mul_f32_e32 v15, 0xbfb8aa3b, v5
	v_exp_f32_e32 v15, v15
	v_fma_f32 v7, -v10, v12, v7
	v_div_fmas_f32 v7, v7, v11, v12
	v_div_fixup_f32 v7, v7, v8, v14
	v_add_f32_e32 v10, 1.0, v15
	v_div_scale_f32 v11, s[24:25], v10, v10, v5
	v_rcp_f32_e32 v12, v11
	v_mul_f32_e32 v6, v6, v7
	v_mul_f32_e32 v7, v13, v9
	v_fma_f32 v8, -v11, v12, 1.0
	v_fmac_f32_e32 v12, v8, v12
	v_div_scale_f32 v8, vcc, v5, v10, v5
	v_mul_f32_e32 v9, v8, v12
	v_fma_f32 v13, -v11, v9, v8
	v_fmac_f32_e32 v9, v13, v12
	v_fma_f32 v8, -v11, v9, v8
	v_div_fmas_f32 v8, v8, v12, v9
	v_div_fixup_f32 v5, v8, v10, v5
	v_mul_f32_e32 v5, v7, v5
	v_cvt_pk_bf16_f32 v5, v6, v5
	s_and_saveexec_b64 s[24:25], s[4:5]
	s_cbranch_execz .Lp4a_s1
	v_ashrrev_i32_e32 v25, 31, v24
	v_lshlrev_b64 v[6:7], 12, v[24:25]
	v_lshl_add_u64 v[6:7], s[12:13], 0, v[6:7]
	v_lshl_add_u64 v[6:7], v[26:27], 1, v[6:7]
	global_store_dwordx4 v[6:7], v[2:5], off
.Lp4a_s1:
	s_or_b64 exec, exec, s[24:25]
	v_add_u32_e32 v22, s41, v206
	v_lshlrev_b32_e32 v0, 3, v22
	v_mul_hi_i32 v2, v22, s53
	v_lshrrev_b32_e32 v3, 31, v2
	v_ashrrev_i32_e32 v2, 4, v2
	v_add_u32_e32 v28, v2, v3
	s_movk_i32 s4, 0xfd00
	v_mad_u64_u32 v[2:3], s[4:5], v28, s4, v[0:1]
	v_ashrrev_i32_e32 v3, 31, v2
	v_readlane_b32 s24, v252, 37
	v_lshlrev_b64 v[30:31], 1, v[2:3]
	v_readlane_b32 s25, v252, 38
	s_movk_i32 s14, 0x600
	s_mov_b32 s26, 0xc00000
	v_lshl_add_u64 v[2:3], s[24:25], 0, v[30:31]
	v_mad_i64_i32 v[2:3], s[4:5], v28, s14, v[2:3]
	v_add_co_u32_e32 v4, vcc, s26, v2
	s_mov_b32 s27, 0x1800000
	s_nop 0
	v_addc_co_u32_e32 v5, vcc, 0, v3, vcc
	global_load_dwordx4 v[32:35], v[2:3], off
	global_load_dwordx4 v[36:39], v[4:5], off
	v_add_co_u32_e32 v2, vcc, s27, v2
	s_mov_b32 s36, 0xc0000
	s_nop 0
	v_addc_co_u32_e32 v3, vcc, 0, v3, vcc
	global_load_dwordx4 v[40:43], v[2:3], off
	v_mov_b64_e32 v[2:3], s[0:1]
	v_mad_i64_i32 v[4:5], s[4:5], v28, s35, v[2:3]
	v_readlane_b32 s4, v254, 7
	s_movk_i32 s9, 0x60
	v_lshl_add_u64 v[4:5], v[4:5], 0, v[30:31]
	v_add_u32_e32 v6, s4, v22
	v_cmp_gt_i32_e64 s[4:5], s36, v6
	v_add_co_u32_e32 v4, vcc, s34, v4
	s_nop 0
	v_cndmask_b32_e64 v6, v82, v6, s[4:5]
	v_mul_hi_i32 v7, v6, s53
	v_lshrrev_b32_e32 v8, 31, v7
	v_ashrrev_i32_e32 v7, 4, v7
	v_add_u32_e32 v24, v7, v8
	v_mul_lo_u32 v7, v24, s9
	v_sub_u32_e32 v23, v6, v7
	v_lshlrev_b32_e32 v26, 3, v23
	v_ashrrev_i32_e32 v27, 31, v26
	v_lshlrev_b64 v[44:45], 1, v[26:27]
	v_addc_co_u32_e32 v5, vcc, 0, v5, vcc
	v_lshl_add_u64 v[6:7], s[24:25], 0, v[44:45]
	v_mad_i64_i32 v[6:7], s[24:25], v24, s14, v[6:7]
	global_load_dwordx4 v[18:21], v[4:5], off offset:512
	s_waitcnt lgkmcnt(0)
	global_load_dwordx4 v[14:17], v[6:7], off
	v_add_co_u32_e32 v4, vcc, s26, v6
	v_mad_i64_i32 v[2:3], s[24:25], v24, s35, v[2:3]
	s_movk_i32 s9, 0xffa0
	v_addc_co_u32_e32 v5, vcc, 0, v7, vcc
	v_lshl_add_u64 v[2:3], v[2:3], 0, v[44:45]
	v_mad_u64_u32 v[44:45], s[24:25], v28, s9, v[22:23]
	global_load_dwordx4 v[10:13], v[4:5], off
	v_add_co_u32_e32 v4, vcc, s27, v6
	v_ashrrev_i32_e32 v44, 3, v44
	v_readlane_b32 s26, v252, 39
	v_addc_co_u32_e32 v5, vcc, 0, v7, vcc
	v_ashrrev_i32_e32 v45, 31, v44
	v_readlane_b32 s27, v252, 40
	v_add_co_u32_e32 v2, vcc, s34, v2
	s_nop 0
	v_lshl_add_u64 v[44:45], v[44:45], 2, s[26:27]
	v_addc_co_u32_e32 v3, vcc, 0, v3, vcc
	v_mad_i64_i32 v[44:45], s[24:25], v28, 48, v[44:45]
	s_mov_b32 s9, 0x60000
	v_add_co_u32_e32 v46, vcc, s9, v44
	global_load_dwordx4 v[6:9], v[4:5], off
	s_nop 0
	v_addc_co_u32_e32 v47, vcc, 0, v45, vcc
	global_load_dword v25, v[44:45], off
	global_load_dword v50, v[46:47], off
	v_ashrrev_i32_e32 v46, 3, v23
	global_load_dwordx4 v[2:5], v[2:3], off offset:512
	v_ashrrev_i32_e32 v47, 31, v46
	v_add_co_u32_e32 v44, vcc, s36, v44
	v_lshl_add_u64 v[46:47], v[46:47], 2, s[26:27]
	s_nop 0
	v_addc_co_u32_e32 v45, vcc, 0, v45, vcc
	v_mad_i64_i32 v[46:47], s[24:25], v24, 48, v[46:47]
	v_add_co_u32_e32 v48, vcc, s9, v46
	global_load_dword v44, v[44:45], off
	s_nop 0
	v_addc_co_u32_e32 v49, vcc, 0, v47, vcc
	global_load_dword v23, v[48:49], off
	s_nop 0
	global_load_dword v48, v[46:47], off
	v_add_co_u32_e32 v46, vcc, s36, v46
	v_ashrrev_i32_e32 v29, 31, v28
	s_nop 0
	v_addc_co_u32_e32 v47, vcc, 0, v47, vcc
	global_load_dword v46, v[46:47], off
	s_waitcnt vmcnt(24)
	s_nop 0
	v_lshlrev_b32_e32 v229, 16, v216
	v_and_b32_e32 v216, 0xffff0000, v216
	v_add_f32_e32 v216, 0, v216
	v_lshlrev_b32_e32 v231, 16, v217
	v_and_b32_e32 v217, 0xffff0000, v217
	v_lshlrev_b32_e32 v236, 16, v220
	v_and_b32_e32 v220, 0xffff0000, v220
	v_add_f32_e32 v217, 0, v217
	v_lshlrev_b32_e32 v233, 16, v218
	v_and_b32_e32 v218, 0xffff0000, v218
	v_add_f32_e32 v216, v216, v220
	v_lshlrev_b32_e32 v220, 16, v221
	v_and_b32_e32 v221, 0xffff0000, v221
	v_add_f32_e32 v218, 0, v218
	v_lshlrev_b32_e32 v235, 16, v219
	v_and_b32_e32 v219, 0xffff0000, v219
	v_add_f32_e32 v217, v217, v221
	v_lshlrev_b32_e32 v221, 16, v222
	v_and_b32_e32 v222, 0xffff0000, v222
	v_add_f32_e32 v219, 0, v219
	v_add_f32_e32 v218, v218, v222
	v_lshlrev_b32_e32 v222, 16, v223
	v_and_b32_e32 v223, 0xffff0000, v223
	v_add_f32_e32 v231, 0, v231
	v_add_f32_e32 v219, v219, v223
	v_lshlrev_b32_e32 v223, 16, v224
	v_and_b32_e32 v224, 0xffff0000, v224
	v_add_f32_e32 v220, v231, v220
	v_add_f32_e32 v216, v216, v224
	v_lshlrev_b32_e32 v224, 16, v225
	v_add_f32_e32 v233, 0, v233
	v_add_f32_e32 v220, v220, v224
	v_and_b32_e32 v224, 0xffff0000, v225
	v_add_f32_e32 v221, v233, v221
	v_add_f32_e32 v217, v217, v224
	v_lshlrev_b32_e32 v224, 16, v226
	v_lshlrev_b32_e32 v225, 16, v202
	v_add_f32_e32 v221, v221, v224
	v_and_b32_e32 v224, 0xffff0000, v226
	v_mul_f32_e32 v226, 0xbfb8aa3b, v225
	v_exp_f32_e32 v226, v226
	v_add_f32_e32 v235, 0, v235
	v_add_f32_e32 v222, v235, v222
	v_add_f32_e32 v218, v218, v224
	v_lshlrev_b32_e32 v224, 16, v227
	v_add_f32_e32 v229, 0, v229
	v_add_f32_e32 v222, v222, v224
	v_add_f32_e32 v224, 1.0, v226
	v_add_f32_e32 v229, v229, v236
	v_div_scale_f32 v226, s[24:25], v224, v224, v225
	v_add_f32_e32 v223, v229, v223
	v_rcp_f32_e32 v229, v226
	v_and_b32_e32 v202, 0xffff0000, v202
	s_waitcnt vmcnt(19)
	v_add_f32_e32 v240, v209, v234
	v_mul_f32_e32 v231, 0xbfb8aa3b, v202
	v_fma_f32 v209, -v226, v229, 1.0
	v_and_b32_e32 v227, 0xffff0000, v227
	v_fmac_f32_e32 v229, v209, v229
	v_div_scale_f32 v209, vcc, v225, v224, v225
	v_exp_f32_e32 v231, v231
	v_add_f32_e32 v219, v219, v227
	v_mul_f32_e32 v227, v209, v229
	v_fma_f32 v233, -v226, v227, v209
	v_fmac_f32_e32 v227, v233, v229
	v_fma_f32 v209, -v226, v227, v209
	v_add_f32_e32 v226, 1.0, v231
	v_div_scale_f32 v231, s[24:25], v226, v226, v202
	v_rcp_f32_e32 v233, v231
	v_div_fmas_f32 v209, v209, v229, v227
	v_lshlrev_b32_e32 v227, 16, v203
	v_mul_f32_e32 v229, 0xbfb8aa3b, v227
	v_div_fixup_f32 v209, v209, v224, v225
	v_fma_f32 v224, -v231, v233, 1.0
	v_exp_f32_e32 v229, v229
	v_fmac_f32_e32 v233, v224, v233
	v_div_scale_f32 v224, vcc, v202, v226, v202
	v_mul_f32_e32 v225, v224, v233
	v_fma_f32 v234, -v231, v225, v224
	v_fmac_f32_e32 v225, v234, v233
	v_add_f32_e32 v229, 1.0, v229
	v_fma_f32 v224, -v231, v225, v224
	v_div_scale_f32 v231, s[24:25], v229, v229, v227
	v_rcp_f32_e32 v234, v231
	v_div_fmas_f32 v224, v224, v233, v225
	v_and_b32_e32 v203, 0xffff0000, v203
	v_div_fixup_f32 v224, v224, v226, v202
	v_mul_f32_e32 v226, 0xbfb8aa3b, v203
	v_fma_f32 v202, -v231, v234, 1.0
	v_exp_f32_e32 v226, v226
	v_fmac_f32_e32 v234, v202, v234
	v_div_scale_f32 v202, vcc, v227, v229, v227
	v_mul_f32_e32 v225, v202, v234
	v_fma_f32 v233, -v231, v225, v202
	v_fmac_f32_e32 v225, v233, v234
	v_add_f32_e32 v226, 1.0, v226
	v_fma_f32 v202, -v231, v225, v202
	v_div_scale_f32 v231, s[24:25], v226, v226, v203
	v_rcp_f32_e32 v233, v231
	v_div_fmas_f32 v202, v202, v234, v225
	v_div_fixup_f32 v225, v202, v229, v227
	v_lshlrev_b32_e32 v229, 16, v204
	v_fma_f32 v202, -v231, v233, 1.0
	v_mul_f32_e32 v234, 0xbfb8aa3b, v229
	v_fmac_f32_e32 v233, v202, v233
	v_div_scale_f32 v202, vcc, v203, v226, v203
	v_exp_f32_e32 v234, v234
	v_mul_f32_e32 v227, v202, v233
	v_fma_f32 v235, -v231, v227, v202
	v_fmac_f32_e32 v227, v235, v233
	v_fma_f32 v202, -v231, v227, v202
	v_add_f32_e32 v231, 1.0, v234
	v_div_scale_f32 v234, s[24:25], v231, v231, v229
	v_rcp_f32_e32 v235, v234
	v_and_b32_e32 v204, 0xffff0000, v204
	v_div_fmas_f32 v202, v202, v233, v227
	v_mul_f32_e32 v227, 0xbfb8aa3b, v204
	v_exp_f32_e32 v227, v227
	v_div_fixup_f32 v226, v202, v226, v203
	v_fma_f32 v202, -v234, v235, 1.0
	v_fmac_f32_e32 v235, v202, v235
	v_div_scale_f32 v202, vcc, v229, v231, v229
	v_mul_f32_e32 v203, v202, v235
	v_fma_f32 v233, -v234, v203, v202
	v_add_f32_e32 v227, 1.0, v227
	v_fmac_f32_e32 v203, v233, v235
	v_div_scale_f32 v233, s[24:25], v227, v227, v204
	v_fma_f32 v202, -v234, v203, v202
	v_rcp_f32_e32 v234, v233
	v_div_fmas_f32 v202, v202, v235, v203
	v_lshlrev_b32_e32 v236, 16, v205
	v_div_fixup_f32 v231, v202, v231, v229
	v_fma_f32 v202, -v233, v234, 1.0
	v_mul_f32_e32 v203, 0xbfb8aa3b, v236
	v_fmac_f32_e32 v234, v202, v234
	v_div_scale_f32 v202, vcc, v204, v227, v204
	v_exp_f32_e32 v229, v203
	v_mul_f32_e32 v235, v202, v234
	v_fma_f32 v203, -v233, v235, v202
	v_fmac_f32_e32 v235, v203, v234
	v_fma_f32 v233, -v233, v235, v202
	s_waitcnt vmcnt(17)
	v_pk_add_f32 v[202:203], v[240:241], v[228:229]
	v_div_fmas_f32 v233, v233, v234, v235
	v_div_scale_f32 v228, s[24:25], v203, v203, v236
	v_rcp_f32_e32 v229, v228
	v_div_fixup_f32 v204, v233, v227, v204
	v_and_b32_e32 v205, 0xffff0000, v205
	v_fma_f32 v227, -v228, v229, 1.0
	v_fmac_f32_e32 v229, v227, v229
	v_div_scale_f32 v227, vcc, v236, v203, v236
	v_mul_f32_e32 v233, v227, v229
	v_fma_f32 v234, -v228, v233, v227
	v_fmac_f32_e32 v233, v234, v229
	v_fma_f32 v227, -v228, v233, v227
	v_div_scale_f32 v228, s[24:25], v202, v202, 1.0
	v_rcp_f32_e32 v234, v228
	v_div_fmas_f32 v227, v227, v229, v233
	v_div_fixup_f32 v227, v227, v203, v236
	v_lshlrev_b64 v[212:213], 12, v[212:213]
	v_fma_f32 v203, -v228, v234, 1.0
	v_fmac_f32_e32 v234, v203, v234
	v_div_scale_f32 v203, vcc, 1.0, v202, 1.0
	v_mul_f32_e32 v229, v203, v234
	v_fma_f32 v233, -v228, v229, v203
	v_fmac_f32_e32 v229, v233, v234
	v_fma_f32 v203, -v228, v229, v203
	v_div_fmas_f32 v203, v203, v234, v229
	v_div_fixup_f32 v228, v203, v202, 1.0
	v_mul_f32_e32 v202, v228, v223
	v_mul_f32_e32 v203, v228, v216
	v_mul_f32_e32 v202, v202, v209
	v_mul_f32_e32 v203, v203, v224
	v_mul_f32_e32 v216, 0xbfb8aa3b, v205
	v_cvt_pk_bf16_f32 v202, v202, v203
	v_mul_f32_e32 v203, v228, v220
	v_mul_f32_e32 v209, v228, v217
	v_exp_f32_e32 v216, v216
	v_mul_f32_e32 v203, v203, v225
	v_mul_f32_e32 v209, v209, v226
	v_cvt_pk_bf16_f32 v203, v203, v209
	v_mul_f32_e32 v209, v228, v221
	v_mul_f32_e32 v217, v228, v218
	v_mul_f32_e32 v209, v209, v231
	v_mul_f32_e32 v204, v217, v204
	v_cvt_pk_bf16_f32 v204, v209, v204
	v_add_f32_e32 v209, 1.0, v216
	v_div_scale_f32 v216, s[24:25], v209, v209, v205
	v_rcp_f32_e32 v217, v216
	v_mul_f32_e32 v218, v228, v222
	v_mul_f32_e32 v219, v228, v219
	v_lshl_add_u64 v[212:213], s[12:13], 0, v[212:213]
	v_fma_f32 v220, -v216, v217, 1.0
	v_fmac_f32_e32 v217, v220, v217
	v_div_scale_f32 v220, vcc, v205, v209, v205
	v_mul_f32_e32 v221, v220, v217
	v_fma_f32 v222, -v216, v221, v220
	v_fmac_f32_e32 v221, v222, v217
	v_fma_f32 v216, -v216, v221, v220
	v_div_fmas_f32 v216, v216, v217, v221
	v_div_fixup_f32 v205, v216, v209, v205
	v_mul_f32_e32 v205, v219, v205
	v_lshl_add_u64 v[212:213], v[212:213], 0, v[214:215]
	v_mul_f32_e32 v218, v218, v227
	v_cvt_pk_bf16_f32 v205, v218, v205
	global_store_dwordx4 v[212:213], v[202:205], off
	v_lshlrev_b32_e32 v209, 16, v152
	v_and_b32_e32 v152, 0xffff0000, v152
	v_lshlrev_b32_e32 v202, 16, v156
	v_and_b32_e32 v156, 0xffff0000, v156
	v_add_f32_e32 v156, 0, v156
	v_lshlrev_b32_e32 v203, 16, v157
	v_and_b32_e32 v157, 0xffff0000, v157
	v_add_f32_e32 v157, 0, v157
	v_lshlrev_b32_e32 v204, 16, v158
	v_and_b32_e32 v158, 0xffff0000, v158
	v_add_f32_e32 v152, v156, v152
	v_lshlrev_b32_e32 v156, 16, v153
	v_and_b32_e32 v153, 0xffff0000, v153
	v_add_f32_e32 v158, 0, v158
	v_lshlrev_b32_e32 v205, 16, v159
	v_and_b32_e32 v159, 0xffff0000, v159
	v_add_f32_e32 v153, v157, v153
	v_lshlrev_b32_e32 v157, 16, v154
	v_and_b32_e32 v154, 0xffff0000, v154
	v_add_f32_e32 v159, 0, v159
	v_add_f32_e32 v154, v158, v154
	v_lshlrev_b32_e32 v158, 16, v155
	v_and_b32_e32 v155, 0xffff0000, v155
	v_add_f32_e32 v203, 0, v203
	v_add_f32_e32 v155, v159, v155
	v_lshlrev_b32_e32 v159, 16, v148
	v_and_b32_e32 v148, 0xffff0000, v148
	v_add_f32_e32 v156, v203, v156
	v_add_f32_e32 v148, v152, v148
	v_lshlrev_b32_e32 v152, 16, v149
	v_add_f32_e32 v204, 0, v204
	v_add_f32_e32 v152, v156, v152
	v_and_b32_e32 v149, 0xffff0000, v149
	s_waitcnt vmcnt(16)
	v_add_f32_e32 v156, v232, v207
	v_add_f32_e32 v202, 0, v202
	v_add_f32_e32 v157, v204, v157
	v_add_f32_e32 v149, v153, v149
	v_lshlrev_b32_e32 v153, 16, v150
	s_waitcnt vmcnt(15)
	v_add_f32_e32 v156, v156, v230
	v_add_f32_e32 v202, v202, v209
	v_add_f32_e32 v153, v157, v153
	v_div_scale_f32 v157, s[24:25], v156, v156, 1.0
	v_add_f32_e32 v159, v202, v159
	v_rcp_f32_e32 v202, v157
	v_and_b32_e32 v150, 0xffff0000, v150
	v_add_f32_e32 v150, v154, v150
	v_lshlrev_b32_e32 v154, 16, v151
	v_and_b32_e32 v151, 0xffff0000, v151
	v_lshlrev_b32_e32 v203, 16, v144
	v_add_f32_e32 v205, 0, v205
	v_add_f32_e32 v151, v155, v151
	v_fma_f32 v155, -v157, v202, 1.0
	v_mul_f32_e32 v204, 0xbfb8aa3b, v203
	v_add_f32_e32 v158, v205, v158
	v_fmac_f32_e32 v202, v155, v202
	v_div_scale_f32 v155, vcc, 1.0, v156, 1.0
	v_exp_f32_e32 v204, v204
	v_add_f32_e32 v154, v158, v154
	v_mul_f32_e32 v158, v155, v202
	v_fma_f32 v205, -v157, v158, v155
	v_fmac_f32_e32 v158, v205, v202
	v_fma_f32 v155, -v157, v158, v155
	v_add_f32_e32 v157, 1.0, v204
	v_div_scale_f32 v204, s[24:25], v157, v157, v203
	v_rcp_f32_e32 v205, v204
	v_div_fmas_f32 v155, v155, v202, v158
	v_div_fixup_f32 v155, v155, v156, 1.0
	v_mul_f32_e32 v156, v155, v159
	v_fma_f32 v158, -v204, v205, 1.0
	v_fmac_f32_e32 v205, v158, v205
	v_div_scale_f32 v158, vcc, v203, v157, v203
	v_mul_f32_e32 v159, v158, v205
	v_fma_f32 v202, -v204, v159, v158
	v_and_b32_e32 v144, 0xffff0000, v144
	v_fmac_f32_e32 v159, v202, v205
	v_mul_f32_e32 v202, 0xbfb8aa3b, v144
	v_exp_f32_e32 v202, v202
	v_fma_f32 v158, -v204, v159, v158
	v_div_fmas_f32 v158, v158, v205, v159
	v_div_fixup_f32 v157, v158, v157, v203
	v_add_f32_e32 v159, 1.0, v202
	v_div_scale_f32 v202, s[24:25], v159, v159, v144
	v_rcp_f32_e32 v204, v202
	v_mul_f32_e32 v156, v156, v157
	v_mul_f32_e32 v148, v155, v148
	v_mul_f32_e32 v149, v155, v149
	v_fma_f32 v157, -v202, v204, 1.0
	v_fmac_f32_e32 v204, v157, v204
	v_div_scale_f32 v157, vcc, v144, v159, v144
	v_mul_f32_e32 v158, v157, v204
	v_fma_f32 v203, -v202, v158, v157
	v_fmac_f32_e32 v158, v203, v204
	v_fma_f32 v157, -v202, v158, v157
	v_lshlrev_b32_e32 v202, 16, v145
	v_mul_f32_e32 v203, 0xbfb8aa3b, v202
	v_exp_f32_e32 v203, v203
	v_div_fmas_f32 v157, v157, v204, v158
	v_div_fixup_f32 v144, v157, v159, v144
	v_mul_f32_e32 v144, v148, v144
	v_add_f32_e32 v157, 1.0, v203
	v_div_scale_f32 v158, s[24:25], v157, v157, v202
	v_rcp_f32_e32 v159, v158
	v_mul_f32_e32 v148, v155, v152
	v_cvt_pk_bf16_f32 v144, v156, v144
	v_and_b32_e32 v145, 0xffff0000, v145
	v_fma_f32 v152, -v158, v159, 1.0
	v_fmac_f32_e32 v159, v152, v159
	v_div_scale_f32 v152, vcc, v202, v157, v202
	v_mul_f32_e32 v156, v152, v159
	v_fma_f32 v203, -v158, v156, v152
	v_fmac_f32_e32 v156, v203, v159
	v_mul_f32_e32 v203, 0xbfb8aa3b, v145
	v_exp_f32_e32 v203, v203
	v_fma_f32 v152, -v158, v156, v152
	v_div_fmas_f32 v152, v152, v159, v156
	v_div_fixup_f32 v152, v152, v157, v202
	v_add_f32_e32 v156, 1.0, v203
	v_div_scale_f32 v158, s[24:25], v156, v156, v145
	v_rcp_f32_e32 v159, v158
	v_mul_f32_e32 v148, v148, v152
	v_fma_f32 v152, -v158, v159, 1.0
	v_fmac_f32_e32 v159, v152, v159
	v_div_scale_f32 v152, vcc, v145, v156, v145
	v_mul_f32_e32 v157, v152, v159
	v_fma_f32 v202, -v158, v157, v152
	v_fmac_f32_e32 v157, v202, v159
	v_fma_f32 v152, -v158, v157, v152
	v_lshlrev_b32_e32 v158, 16, v146
	v_mul_f32_e32 v202, 0xbfb8aa3b, v158
	v_exp_f32_e32 v202, v202
	v_div_fmas_f32 v152, v152, v159, v157
	v_div_fixup_f32 v145, v152, v156, v145
	v_mul_f32_e32 v145, v149, v145
	v_add_f32_e32 v152, 1.0, v202
	v_div_scale_f32 v156, s[24:25], v152, v152, v158
	v_rcp_f32_e32 v157, v156
	v_cvt_pk_bf16_f32 v145, v148, v145
	v_mul_f32_e32 v148, v155, v153
	v_and_b32_e32 v146, 0xffff0000, v146
	v_fma_f32 v149, -v156, v157, 1.0
	v_fmac_f32_e32 v157, v149, v157
	v_div_scale_f32 v149, vcc, v158, v152, v158
	v_mul_f32_e32 v153, v149, v157
	v_fma_f32 v159, -v156, v153, v149
	v_fmac_f32_e32 v153, v159, v157
	v_mul_f32_e32 v159, 0xbfb8aa3b, v146
	v_exp_f32_e32 v159, v159
	v_fma_f32 v149, -v156, v153, v149
	v_div_fmas_f32 v149, v149, v157, v153
	v_div_fixup_f32 v149, v149, v152, v158
	v_add_f32_e32 v153, 1.0, v159
	v_div_scale_f32 v156, s[24:25], v153, v153, v146
	v_rcp_f32_e32 v157, v156
	v_mul_f32_e32 v148, v148, v149
	v_mul_f32_e32 v149, v155, v150
	v_fma_f32 v150, -v156, v157, 1.0
	v_fmac_f32_e32 v157, v150, v157
	v_div_scale_f32 v150, vcc, v146, v153, v146
	v_mul_f32_e32 v152, v150, v157
	v_fma_f32 v158, -v156, v152, v150
	v_fmac_f32_e32 v152, v158, v157
	v_fma_f32 v150, -v156, v152, v150
	v_lshlrev_b32_e32 v156, 16, v147
	v_mul_f32_e32 v158, 0xbfb8aa3b, v156
	v_exp_f32_e32 v158, v158
	v_div_fmas_f32 v150, v150, v157, v152
	v_div_fixup_f32 v146, v150, v153, v146
	v_mul_f32_e32 v146, v149, v146
	v_add_f32_e32 v150, 1.0, v158
	v_div_scale_f32 v152, s[24:25], v150, v150, v156
	v_rcp_f32_e32 v153, v152
	v_cvt_pk_bf16_f32 v146, v148, v146
	v_mul_f32_e32 v148, v155, v154
	v_and_b32_e32 v147, 0xffff0000, v147
	v_fma_f32 v149, -v152, v153, 1.0
	v_fmac_f32_e32 v153, v149, v153
	v_div_scale_f32 v149, vcc, v156, v150, v156
	v_mul_f32_e32 v154, v149, v153
	v_fma_f32 v157, -v152, v154, v149
	v_fmac_f32_e32 v154, v157, v153
	v_mul_f32_e32 v157, 0xbfb8aa3b, v147
	v_exp_f32_e32 v157, v157
	v_fma_f32 v149, -v152, v154, v149
	v_div_fmas_f32 v149, v149, v153, v154
	v_div_fixup_f32 v149, v149, v150, v156
	v_add_f32_e32 v152, 1.0, v157
	v_div_scale_f32 v153, s[24:25], v152, v152, v147
	v_rcp_f32_e32 v154, v153
	v_mul_f32_e32 v148, v148, v149
	v_mul_f32_e32 v149, v155, v151
	v_fma_f32 v150, -v153, v154, 1.0
	v_fmac_f32_e32 v154, v150, v154
	v_div_scale_f32 v150, vcc, v147, v152, v147
	v_mul_f32_e32 v151, v150, v154
	v_fma_f32 v155, -v153, v151, v150
	v_fmac_f32_e32 v151, v155, v154
	v_fma_f32 v150, -v153, v151, v150
	v_div_fmas_f32 v150, v150, v154, v151
	v_div_fixup_f32 v147, v150, v152, v147
	v_mul_f32_e32 v147, v149, v147
	v_cvt_pk_bf16_f32 v147, v148, v147
	s_and_saveexec_b64 s[24:25], s[38:39]
	s_cbranch_execz .Lp4a_s2
	v_ashrrev_i32_e32 v209, 31, v208
	v_lshlrev_b64 v[148:149], 12, v[208:209]
	v_lshl_add_u64 v[148:149], s[12:13], 0, v[148:149]
	v_lshl_add_u64 v[148:149], v[210:211], 1, v[148:149]
	global_store_dwordx4 v[148:149], v[144:147], off
.Lp4a_s2:
	s_or_b64 exec, exec, s[24:25]
	s_waitcnt vmcnt(10)
	s_nop 0
	v_lshlrev_b32_e32 v45, 16, v32
	v_and_b32_e32 v32, 0xffff0000, v32
	v_add_f32_e32 v32, 0, v32
	v_lshlrev_b32_e32 v47, 16, v33
	v_and_b32_e32 v33, 0xffff0000, v33
	v_lshlrev_b32_e32 v52, 16, v36
	v_and_b32_e32 v36, 0xffff0000, v36
	v_add_f32_e32 v33, 0, v33
	v_lshlrev_b32_e32 v49, 16, v34
	v_and_b32_e32 v34, 0xffff0000, v34
	v_add_f32_e32 v32, v32, v36
	v_lshlrev_b32_e32 v36, 16, v37
	v_and_b32_e32 v37, 0xffff0000, v37
	v_add_f32_e32 v34, 0, v34
	v_lshlrev_b32_e32 v51, 16, v35
	v_and_b32_e32 v35, 0xffff0000, v35
	v_add_f32_e32 v33, v33, v37
	v_lshlrev_b32_e32 v37, 16, v38
	v_and_b32_e32 v38, 0xffff0000, v38
	v_add_f32_e32 v35, 0, v35
	v_add_f32_e32 v34, v34, v38
	v_lshlrev_b32_e32 v38, 16, v39
	v_and_b32_e32 v39, 0xffff0000, v39
	v_add_f32_e32 v47, 0, v47
	v_add_f32_e32 v35, v35, v39
	v_lshlrev_b32_e32 v39, 16, v40
	v_and_b32_e32 v40, 0xffff0000, v40
	v_add_f32_e32 v36, v47, v36
	v_add_f32_e32 v32, v32, v40
	v_lshlrev_b32_e32 v40, 16, v41
	v_add_f32_e32 v49, 0, v49
	v_add_f32_e32 v36, v36, v40
	v_and_b32_e32 v40, 0xffff0000, v41
	v_add_f32_e32 v37, v49, v37
	v_add_f32_e32 v33, v33, v40
	v_lshlrev_b32_e32 v40, 16, v42
	v_lshlrev_b32_e32 v41, 16, v18
	v_add_f32_e32 v37, v37, v40
	v_and_b32_e32 v40, 0xffff0000, v42
	v_mul_f32_e32 v42, 0xbfb8aa3b, v41
	v_exp_f32_e32 v42, v42
	v_add_f32_e32 v51, 0, v51
	v_add_f32_e32 v38, v51, v38
	v_add_f32_e32 v34, v34, v40
	v_lshlrev_b32_e32 v40, 16, v43
	v_add_f32_e32 v45, 0, v45
	v_add_f32_e32 v38, v38, v40
	v_add_f32_e32 v40, 1.0, v42
	v_add_f32_e32 v45, v45, v52
	v_div_scale_f32 v42, s[24:25], v40, v40, v41
	v_add_f32_e32 v39, v45, v39
	v_rcp_f32_e32 v45, v42
	v_and_b32_e32 v18, 0xffff0000, v18
	s_waitcnt vmcnt(5)
	v_add_f32_e32 v176, v25, v50
	v_mul_f32_e32 v47, 0xbfb8aa3b, v18
	v_fma_f32 v25, -v42, v45, 1.0
	v_and_b32_e32 v43, 0xffff0000, v43
	v_fmac_f32_e32 v45, v25, v45
	v_div_scale_f32 v25, vcc, v41, v40, v41
	v_exp_f32_e32 v47, v47
	v_add_f32_e32 v35, v35, v43
	v_mul_f32_e32 v43, v25, v45
	v_fma_f32 v49, -v42, v43, v25
	v_fmac_f32_e32 v43, v49, v45
	v_fma_f32 v25, -v42, v43, v25
	v_add_f32_e32 v42, 1.0, v47
	v_div_scale_f32 v47, s[24:25], v42, v42, v18
	v_rcp_f32_e32 v49, v47
	v_div_fmas_f32 v25, v25, v45, v43
	v_lshlrev_b32_e32 v43, 16, v19
	v_mul_f32_e32 v45, 0xbfb8aa3b, v43
	v_div_fixup_f32 v25, v25, v40, v41
	v_fma_f32 v40, -v47, v49, 1.0
	v_exp_f32_e32 v45, v45
	v_fmac_f32_e32 v49, v40, v49
	v_div_scale_f32 v40, vcc, v18, v42, v18
	v_mul_f32_e32 v41, v40, v49
	v_fma_f32 v50, -v47, v41, v40
	v_fmac_f32_e32 v41, v50, v49
	v_add_f32_e32 v45, 1.0, v45
	v_fma_f32 v40, -v47, v41, v40
	v_div_scale_f32 v47, s[24:25], v45, v45, v43
	v_rcp_f32_e32 v50, v47
	v_div_fmas_f32 v40, v40, v49, v41
	v_and_b32_e32 v19, 0xffff0000, v19
	v_div_fixup_f32 v40, v40, v42, v18
	v_mul_f32_e32 v42, 0xbfb8aa3b, v19
	v_fma_f32 v18, -v47, v50, 1.0
	v_exp_f32_e32 v42, v42
	v_fmac_f32_e32 v50, v18, v50
	v_div_scale_f32 v18, vcc, v43, v45, v43
	v_mul_f32_e32 v41, v18, v50
	v_fma_f32 v49, -v47, v41, v18
	v_fmac_f32_e32 v41, v49, v50
	v_add_f32_e32 v42, 1.0, v42
	v_fma_f32 v18, -v47, v41, v18
	v_div_scale_f32 v47, s[24:25], v42, v42, v19
	v_rcp_f32_e32 v49, v47
	v_div_fmas_f32 v18, v18, v50, v41
	v_div_fixup_f32 v41, v18, v45, v43
	v_lshlrev_b32_e32 v45, 16, v20
	v_fma_f32 v18, -v47, v49, 1.0
	v_mul_f32_e32 v50, 0xbfb8aa3b, v45
	v_fmac_f32_e32 v49, v18, v49
	v_div_scale_f32 v18, vcc, v19, v42, v19
	v_exp_f32_e32 v50, v50
	v_mul_f32_e32 v43, v18, v49
	v_fma_f32 v51, -v47, v43, v18
	v_fmac_f32_e32 v43, v51, v49
	v_fma_f32 v18, -v47, v43, v18
	v_add_f32_e32 v47, 1.0, v50
	v_div_scale_f32 v50, s[24:25], v47, v47, v45
	v_rcp_f32_e32 v51, v50
	v_and_b32_e32 v20, 0xffff0000, v20
	v_div_fmas_f32 v18, v18, v49, v43
	v_mul_f32_e32 v43, 0xbfb8aa3b, v20
	v_exp_f32_e32 v43, v43
	v_div_fixup_f32 v42, v18, v42, v19
	v_fma_f32 v18, -v50, v51, 1.0
	v_fmac_f32_e32 v51, v18, v51
	v_div_scale_f32 v18, vcc, v45, v47, v45
	v_mul_f32_e32 v19, v18, v51
	v_fma_f32 v49, -v50, v19, v18
	v_add_f32_e32 v43, 1.0, v43
	v_fmac_f32_e32 v19, v49, v51
	v_div_scale_f32 v49, s[24:25], v43, v43, v20
	v_fma_f32 v18, -v50, v19, v18
	v_rcp_f32_e32 v50, v49
	v_div_fmas_f32 v18, v18, v51, v19
	v_lshlrev_b32_e32 v52, 16, v21
	v_div_fixup_f32 v47, v18, v47, v45
	v_fma_f32 v18, -v49, v50, 1.0
	v_mul_f32_e32 v19, 0xbfb8aa3b, v52
	v_fmac_f32_e32 v50, v18, v50
	v_div_scale_f32 v18, vcc, v20, v43, v20
	v_exp_f32_e32 v45, v19
	v_mul_f32_e32 v51, v18, v50
	v_fma_f32 v19, -v49, v51, v18
	v_fmac_f32_e32 v51, v19, v50
	v_fma_f32 v49, -v49, v51, v18
	s_waitcnt vmcnt(3)
	v_pk_add_f32 v[18:19], v[176:177], v[44:45]
	v_div_fmas_f32 v49, v49, v50, v51
	v_div_scale_f32 v44, s[24:25], v19, v19, v52
	v_rcp_f32_e32 v45, v44
	v_div_fixup_f32 v20, v49, v43, v20
	v_and_b32_e32 v21, 0xffff0000, v21
	v_fma_f32 v43, -v44, v45, 1.0
	v_fmac_f32_e32 v45, v43, v45
	v_div_scale_f32 v43, vcc, v52, v19, v52
	v_mul_f32_e32 v49, v43, v45
	v_fma_f32 v50, -v44, v49, v43
	v_fmac_f32_e32 v49, v50, v45
	v_fma_f32 v43, -v44, v49, v43
	v_div_scale_f32 v44, s[24:25], v18, v18, 1.0
	v_rcp_f32_e32 v50, v44
	v_div_fmas_f32 v43, v43, v45, v49
	v_div_fixup_f32 v43, v43, v19, v52
	v_lshlrev_b64 v[28:29], 12, v[28:29]
	v_fma_f32 v19, -v44, v50, 1.0
	v_fmac_f32_e32 v50, v19, v50
	v_div_scale_f32 v19, vcc, 1.0, v18, 1.0
	v_mul_f32_e32 v45, v19, v50
	v_fma_f32 v49, -v44, v45, v19
	v_fmac_f32_e32 v45, v49, v50
	v_fma_f32 v19, -v44, v45, v19
	v_div_fmas_f32 v19, v19, v50, v45
	v_div_fixup_f32 v44, v19, v18, 1.0
	v_mul_f32_e32 v18, v44, v39
	v_mul_f32_e32 v19, v44, v32
	v_mul_f32_e32 v18, v18, v25
	v_mul_f32_e32 v19, v19, v40
	v_mul_f32_e32 v32, 0xbfb8aa3b, v21
	v_cvt_pk_bf16_f32 v18, v18, v19
	v_mul_f32_e32 v19, v44, v36
	v_mul_f32_e32 v25, v44, v33
	v_exp_f32_e32 v32, v32
	v_mul_f32_e32 v19, v19, v41
	v_mul_f32_e32 v25, v25, v42
	v_cvt_pk_bf16_f32 v19, v19, v25
	v_mul_f32_e32 v25, v44, v37
	v_mul_f32_e32 v33, v44, v34
	v_mul_f32_e32 v25, v25, v47
	v_mul_f32_e32 v20, v33, v20
	v_cvt_pk_bf16_f32 v20, v25, v20
	v_add_f32_e32 v25, 1.0, v32
	v_div_scale_f32 v32, s[24:25], v25, v25, v21
	v_rcp_f32_e32 v33, v32
	v_mul_f32_e32 v34, v44, v38
	v_mul_f32_e32 v35, v44, v35
	v_lshl_add_u64 v[28:29], s[12:13], 0, v[28:29]
	v_fma_f32 v36, -v32, v33, 1.0
	v_fmac_f32_e32 v33, v36, v33
	v_div_scale_f32 v36, vcc, v21, v25, v21
	v_mul_f32_e32 v37, v36, v33
	v_fma_f32 v38, -v32, v37, v36
	v_fmac_f32_e32 v37, v38, v33
	v_fma_f32 v32, -v32, v37, v36
	v_div_fmas_f32 v32, v32, v33, v37
	v_div_fixup_f32 v21, v32, v25, v21
	v_mul_f32_e32 v21, v35, v21
	v_lshl_add_u64 v[28:29], v[28:29], 0, v[30:31]
	v_mul_f32_e32 v34, v34, v43
	v_cvt_pk_bf16_f32 v21, v34, v21
	global_store_dwordx4 v[28:29], v[18:21], off
	v_lshlrev_b32_e32 v25, 16, v10
	v_and_b32_e32 v10, 0xffff0000, v10
	v_lshlrev_b32_e32 v18, 16, v14
	v_and_b32_e32 v14, 0xffff0000, v14
	v_add_f32_e32 v14, 0, v14
	v_lshlrev_b32_e32 v19, 16, v15
	v_and_b32_e32 v15, 0xffff0000, v15
	v_add_f32_e32 v15, 0, v15
	v_lshlrev_b32_e32 v20, 16, v16
	v_and_b32_e32 v16, 0xffff0000, v16
	v_add_f32_e32 v10, v14, v10
	v_lshlrev_b32_e32 v14, 16, v11
	v_and_b32_e32 v11, 0xffff0000, v11
	v_add_f32_e32 v16, 0, v16
	v_lshlrev_b32_e32 v21, 16, v17
	v_and_b32_e32 v17, 0xffff0000, v17
	v_add_f32_e32 v11, v15, v11
	v_lshlrev_b32_e32 v15, 16, v12
	v_and_b32_e32 v12, 0xffff0000, v12
	v_add_f32_e32 v17, 0, v17
	v_add_f32_e32 v12, v16, v12
	v_lshlrev_b32_e32 v16, 16, v13
	v_and_b32_e32 v13, 0xffff0000, v13
	v_add_f32_e32 v19, 0, v19
	v_add_f32_e32 v13, v17, v13
	v_lshlrev_b32_e32 v17, 16, v6
	v_and_b32_e32 v6, 0xffff0000, v6
	v_add_f32_e32 v14, v19, v14
	v_add_f32_e32 v6, v10, v6
	v_lshlrev_b32_e32 v10, 16, v7
	v_add_f32_e32 v20, 0, v20
	v_add_f32_e32 v10, v14, v10
	v_and_b32_e32 v7, 0xffff0000, v7
	s_waitcnt vmcnt(2)
	v_add_f32_e32 v14, v48, v23
	v_add_f32_e32 v18, 0, v18
	v_add_f32_e32 v15, v20, v15
	v_add_f32_e32 v7, v11, v7
	v_lshlrev_b32_e32 v11, 16, v8
	s_waitcnt vmcnt(1)
	v_add_f32_e32 v14, v14, v46
	v_add_f32_e32 v18, v18, v25
	v_add_f32_e32 v11, v15, v11
	v_div_scale_f32 v15, s[24:25], v14, v14, 1.0
	v_add_f32_e32 v17, v18, v17
	v_rcp_f32_e32 v18, v15
	v_and_b32_e32 v8, 0xffff0000, v8
	v_add_f32_e32 v8, v12, v8
	v_lshlrev_b32_e32 v12, 16, v9
	v_and_b32_e32 v9, 0xffff0000, v9
	v_lshlrev_b32_e32 v19, 16, v2
	v_add_f32_e32 v21, 0, v21
	v_add_f32_e32 v9, v13, v9
	v_fma_f32 v13, -v15, v18, 1.0
	v_mul_f32_e32 v20, 0xbfb8aa3b, v19
	v_add_f32_e32 v16, v21, v16
	v_fmac_f32_e32 v18, v13, v18
	v_div_scale_f32 v13, vcc, 1.0, v14, 1.0
	v_exp_f32_e32 v20, v20
	v_add_f32_e32 v12, v16, v12
	v_mul_f32_e32 v16, v13, v18
	v_fma_f32 v21, -v15, v16, v13
	v_fmac_f32_e32 v16, v21, v18
	v_fma_f32 v13, -v15, v16, v13
	v_add_f32_e32 v15, 1.0, v20
	v_div_scale_f32 v20, s[24:25], v15, v15, v19
	v_rcp_f32_e32 v21, v20
	v_div_fmas_f32 v13, v13, v18, v16
	v_div_fixup_f32 v13, v13, v14, 1.0
	v_mul_f32_e32 v14, v13, v17
	v_fma_f32 v16, -v20, v21, 1.0
	v_fmac_f32_e32 v21, v16, v21
	v_div_scale_f32 v16, vcc, v19, v15, v19
	v_mul_f32_e32 v17, v16, v21
	v_fma_f32 v18, -v20, v17, v16
	v_and_b32_e32 v2, 0xffff0000, v2
	v_fmac_f32_e32 v17, v18, v21
	v_mul_f32_e32 v18, 0xbfb8aa3b, v2
	v_exp_f32_e32 v18, v18
	v_fma_f32 v16, -v20, v17, v16
	v_div_fmas_f32 v16, v16, v21, v17
	v_div_fixup_f32 v15, v16, v15, v19
	v_add_f32_e32 v17, 1.0, v18
	v_div_scale_f32 v18, s[24:25], v17, v17, v2
	v_rcp_f32_e32 v20, v18
	v_mul_f32_e32 v14, v14, v15
	v_mul_f32_e32 v6, v13, v6
	v_mul_f32_e32 v7, v13, v7
	v_fma_f32 v15, -v18, v20, 1.0
	v_fmac_f32_e32 v20, v15, v20
	v_div_scale_f32 v15, vcc, v2, v17, v2
	v_mul_f32_e32 v16, v15, v20
	v_fma_f32 v19, -v18, v16, v15
	v_fmac_f32_e32 v16, v19, v20
	v_fma_f32 v15, -v18, v16, v15
	v_lshlrev_b32_e32 v18, 16, v3
	v_mul_f32_e32 v19, 0xbfb8aa3b, v18
	v_exp_f32_e32 v19, v19
	v_div_fmas_f32 v15, v15, v20, v16
	v_div_fixup_f32 v2, v15, v17, v2
	v_mul_f32_e32 v2, v6, v2
	v_add_f32_e32 v15, 1.0, v19
	v_div_scale_f32 v16, s[24:25], v15, v15, v18
	v_rcp_f32_e32 v17, v16
	v_mul_f32_e32 v6, v13, v10
	v_cvt_pk_bf16_f32 v2, v14, v2
	v_and_b32_e32 v3, 0xffff0000, v3
	v_fma_f32 v10, -v16, v17, 1.0
	v_fmac_f32_e32 v17, v10, v17
	v_div_scale_f32 v10, vcc, v18, v15, v18
	v_mul_f32_e32 v14, v10, v17
	v_fma_f32 v19, -v16, v14, v10
	v_fmac_f32_e32 v14, v19, v17
	v_mul_f32_e32 v19, 0xbfb8aa3b, v3
	v_exp_f32_e32 v19, v19
	v_fma_f32 v10, -v16, v14, v10
	v_div_fmas_f32 v10, v10, v17, v14
	v_div_fixup_f32 v10, v10, v15, v18
	v_add_f32_e32 v14, 1.0, v19
	v_div_scale_f32 v16, s[24:25], v14, v14, v3
	v_rcp_f32_e32 v17, v16
	v_mul_f32_e32 v6, v6, v10
	v_fma_f32 v10, -v16, v17, 1.0
	v_fmac_f32_e32 v17, v10, v17
	v_div_scale_f32 v10, vcc, v3, v14, v3
	v_mul_f32_e32 v15, v10, v17
	v_fma_f32 v18, -v16, v15, v10
	v_fmac_f32_e32 v15, v18, v17
	v_fma_f32 v10, -v16, v15, v10
	v_lshlrev_b32_e32 v16, 16, v4
	v_mul_f32_e32 v18, 0xbfb8aa3b, v16
	v_exp_f32_e32 v18, v18
	v_div_fmas_f32 v10, v10, v17, v15
	v_div_fixup_f32 v3, v10, v14, v3
	v_mul_f32_e32 v3, v7, v3
	v_add_f32_e32 v10, 1.0, v18
	v_div_scale_f32 v14, s[24:25], v10, v10, v16
	v_rcp_f32_e32 v15, v14
	v_cvt_pk_bf16_f32 v3, v6, v3
	v_mul_f32_e32 v6, v13, v11
	v_and_b32_e32 v4, 0xffff0000, v4
	v_fma_f32 v7, -v14, v15, 1.0
	v_fmac_f32_e32 v15, v7, v15
	v_div_scale_f32 v7, vcc, v16, v10, v16
	v_mul_f32_e32 v11, v7, v15
	v_fma_f32 v17, -v14, v11, v7
	v_fmac_f32_e32 v11, v17, v15
	v_mul_f32_e32 v17, 0xbfb8aa3b, v4
	v_exp_f32_e32 v17, v17
	v_fma_f32 v7, -v14, v11, v7
	v_div_fmas_f32 v7, v7, v15, v11
	v_div_fixup_f32 v7, v7, v10, v16
	v_add_f32_e32 v11, 1.0, v17
	v_div_scale_f32 v14, s[24:25], v11, v11, v4
	v_rcp_f32_e32 v15, v14
	v_mul_f32_e32 v6, v6, v7
	v_mul_f32_e32 v7, v13, v8
	v_fma_f32 v8, -v14, v15, 1.0
	v_fmac_f32_e32 v15, v8, v15
	v_div_scale_f32 v8, vcc, v4, v11, v4
	v_mul_f32_e32 v10, v8, v15
	v_fma_f32 v16, -v14, v10, v8
	v_fmac_f32_e32 v10, v16, v15
	v_fma_f32 v8, -v14, v10, v8
	v_lshlrev_b32_e32 v14, 16, v5
	v_mul_f32_e32 v16, 0xbfb8aa3b, v14
	v_exp_f32_e32 v16, v16
	v_div_fmas_f32 v8, v8, v15, v10
	v_div_fixup_f32 v4, v8, v11, v4
	v_mul_f32_e32 v4, v7, v4
	v_add_f32_e32 v8, 1.0, v16
	v_div_scale_f32 v10, s[24:25], v8, v8, v14
	v_rcp_f32_e32 v11, v10
	v_cvt_pk_bf16_f32 v4, v6, v4
	v_mul_f32_e32 v6, v13, v12
	v_and_b32_e32 v5, 0xffff0000, v5
	v_fma_f32 v7, -v10, v11, 1.0
	v_fmac_f32_e32 v11, v7, v11
	v_div_scale_f32 v7, vcc, v14, v8, v14
	v_mul_f32_e32 v12, v7, v11
	v_fma_f32 v15, -v10, v12, v7
	v_fmac_f32_e32 v12, v15, v11
	v_mul_f32_e32 v15, 0xbfb8aa3b, v5
	v_exp_f32_e32 v15, v15
	v_fma_f32 v7, -v10, v12, v7
	v_div_fmas_f32 v7, v7, v11, v12
	v_div_fixup_f32 v7, v7, v8, v14
	v_add_f32_e32 v10, 1.0, v15
	v_div_scale_f32 v11, s[24:25], v10, v10, v5
	v_rcp_f32_e32 v12, v11
	v_mul_f32_e32 v6, v6, v7
	v_mul_f32_e32 v7, v13, v9
	v_fma_f32 v8, -v11, v12, 1.0
	v_fmac_f32_e32 v12, v8, v12
	v_div_scale_f32 v8, vcc, v5, v10, v5
	v_mul_f32_e32 v9, v8, v12
	v_fma_f32 v13, -v11, v9, v8
	v_fmac_f32_e32 v9, v13, v12
	v_fma_f32 v8, -v11, v9, v8
	v_div_fmas_f32 v8, v8, v12, v9
	v_div_fixup_f32 v5, v8, v10, v5
	v_mul_f32_e32 v5, v7, v5
	v_cvt_pk_bf16_f32 v5, v6, v5
	s_and_saveexec_b64 s[24:25], s[4:5]
	s_cbranch_execz .Lp4a_s3
	v_ashrrev_i32_e32 v25, 31, v24
	v_lshlrev_b64 v[6:7], 12, v[24:25]
	v_lshl_add_u64 v[6:7], s[12:13], 0, v[6:7]
	v_lshl_add_u64 v[6:7], v[26:27], 1, v[6:7]
	global_store_dwordx4 v[6:7], v[2:5], off
.Lp4a_s3:
	s_or_b64 exec, exec, s[24:25]
	s_branch .LBB0_487
	s_branch .LBB0_485
